# ds_bpermute wave reductions in prologue x-pass (rs) and q/k-norm phase replaced by DPP row ops; plus conv/attention/GEMM changes
# speedup vs baseline: 1.0134x; 1.0134x over previous
; __device__ __forceinline__ void x_row_to_bf16(const float* xrow, bf16* orow, float* rs, int lane) {
;     const int lo = lane & 31, hi = lane >> 5;
;     const f32x4* xr = (const f32x4*)xrow + 2 * lo + hi;
;     f32x4 v[8]; float s = 0.f;
; #pragma unroll
;     for (int j = 0; j < 8; ++j) { v[j] = xr[64 * j]; s += (v[j].x * v[j].x + v[j].y * v[j].y) + (v[j].z * v[j].z + v[j].w * v[j].w); }
;     const float rinv = 1.0f / sqrtf(wave_sum(s) * (1.f / DM) + EPS_RMS);
;     if (lane == 0) *rs = rinv;
; __device__ __forceinline__ void p0_prologue(const Ptrs& P, LAS unsigned char* lds, int gw, int NGW, int wave, int lane) {
;     ...
;     for (int m = gw; m < M_TOK; m += NGW) x_row_to_bf16(P.x + (size_t)m * DM, P.XN + (size_t)m * DM, P.RS1 + m, lane);
.LBB0_86:
	s_cmpk_gt_i32 s60, 0x7fff
	s_cbranch_scc1 .LBB0_91
	v_mbcnt_lo_u32_b32 v2, -1, 0
	v_mbcnt_hi_u32_b32 v2, -1, v2
	v_and_b32_e32 v3, 64, v2
	v_add_u32_e32 v3, 64, v3
	v_xor_b32_e32 v4, 1, v2
	v_cmp_lt_i32_e32 vcc, v4, v3
	s_ashr_i32 s61, s60, 31
	s_lshl_b64 s[0:1], s[60:61], 2
	v_cndmask_b32_e32 v4, v2, v4, vcc
	v_lshlrev_b32_e32 v38, 2, v4
	v_xor_b32_e32 v4, 2, v2
	v_cmp_lt_i32_e32 vcc, v4, v3
	s_waitcnt lgkmcnt(0)
	s_add_u32 s40, s0, 0x700000
	s_addc_u32 s41, s1, 0
	v_cndmask_b32_e32 v4, v2, v4, vcc
	v_lshlrev_b32_e32 v39, 2, v4
	v_xor_b32_e32 v4, 4, v2
	v_cmp_lt_i32_e32 vcc, v4, v3
	s_lshl_b64 s[0:1], s[60:61], 13
	s_ashr_i32 s5, s4, 31
	v_cndmask_b32_e32 v4, v2, v4, vcc
	v_lshlrev_b32_e32 v40, 2, v4
	v_xor_b32_e32 v4, 8, v2
	v_cmp_lt_i32_e32 vcc, v4, v3
	v_cmp_eq_u32_e64 s[2:3], 63, v1
	s_lshl_b64 s[24:25], s[4:5], 2
	v_cndmask_b32_e32 v4, v2, v4, vcc
	v_lshlrev_b32_e32 v41, 2, v4
	v_xor_b32_e32 v4, 16, v2
	v_cmp_lt_i32_e32 vcc, v4, v3
	s_lshl_b64 s[26:27], s[4:5], 13
	v_mov_b32_e32 v44, 0x358637bd
	v_cndmask_b32_e32 v4, v2, v4, vcc
	v_lshlrev_b32_e32 v42, 2, v4
	v_xor_b32_e32 v4, 32, v2
	v_cmp_lt_i32_e32 vcc, v4, v3
	v_lshlrev_b32_e32 v3, 4, v67
	v_mov_b32_e32 v45, 0x260
	v_cndmask_b32_e32 v2, v2, v4, vcc
	v_and_b32_e32 v4, 31, v200
	v_lshlrev_b32_e32 v43, 2, v2
	v_lshlrev_b32_e32 v2, 5, v4
	v_or3_b32 v2, s0, v2, v3
	v_mov_b32_e32 v3, s1
	v_lshl_add_u64 v[2:3], s[36:37], 0, v[2:3]
	s_mov_b64 s[0:1], 0x1000
	v_lshl_add_u64 v[34:35], v[2:3], 0, s[0:1]
	s_lshl_b64 s[0:1], s[60:61], 12
	v_lshlrev_b32_e32 v2, 9, v67
	v_lshlrev_b32_e32 v3, 4, v4
	v_or3_b32 v36, s0, v2, v3
	v_mov_b32_e32 v37, s1
	s_lshl_b64 s[36:37], s[4:5], 12
	s_mov_b32 s5, 0xf800000
	s_mov_b32 s52, 0x6800000
	s_mov_b32 s53, s60
	s_branch .LBB0_89

; __device__ __forceinline__ void x_row_to_bf16(const float* xrow, bf16* orow, float* rs, int lane) {
;     const int lo = lane & 31, hi = lane >> 5;
;     const f32x4* xr = (const f32x4*)xrow + 2 * lo + hi;
;     f32x4 v[8]; float s = 0.f;
; #pragma unroll
;     for (int j = 0; j < 8; ++j) { v[j] = xr[64 * j]; s += (v[j].x * v[j].x + v[j].y * v[j].y) + (v[j].z * v[j].z + v[j].w * v[j].w); }
;     const float rinv = 1.0f / sqrtf(wave_sum(s) * (1.f / DM) + EPS_RMS);
;     if (lane == 0) *rs = rinv;
.LBB0_89:
	global_load_dwordx4 v[26:29], v[34:35], off offset:-4096
	global_load_dwordx4 v[30:33], v[34:35], off offset:-3072
	global_load_dwordx4 v[18:21], v[34:35], off offset:-2048
	global_load_dwordx4 v[22:25], v[34:35], off offset:-1024
	global_load_dwordx4 v[10:13], v[34:35], off
	global_load_dwordx4 v[14:17], v[34:35], off offset:1024
	global_load_dwordx4 v[2:5], v[34:35], off offset:2048
	global_load_dwordx4 v[6:9], v[34:35], off offset:3072
	s_waitcnt vmcnt(0)
	v_mul_f32_e32 v46, v27, v27
	s_waitcnt lgkmcnt(0)
	v_mul_f32_e32 v47, v29, v29
	v_mul_f32_e32 v48, v31, v31
	v_mul_f32_e32 v49, v33, v33
	v_mul_f32_e32 v50, v19, v19
	v_mul_f32_e32 v51, v21, v21
	v_fmac_f32_e32 v46, v26, v26
	v_fmac_f32_e32 v47, v28, v28
	v_fmac_f32_e32 v48, v30, v30
	v_fmac_f32_e32 v49, v32, v32
	v_mul_f32_e32 v52, v23, v23
	v_mul_f32_e32 v53, v25, v25
	v_fmac_f32_e32 v50, v18, v18
	v_fmac_f32_e32 v51, v20, v20
	v_add_f32_e32 v46, v46, v47
	v_add_f32_e32 v47, v48, v49
	v_mul_f32_e32 v54, v11, v11
	v_mul_f32_e32 v55, v13, v13
	v_fmac_f32_e32 v52, v22, v22
	v_fmac_f32_e32 v53, v24, v24
	v_add_f32_e32 v48, v50, v51
	v_add_f32_e32 v46, v46, v47
	v_mul_f32_e32 v56, v15, v15
	v_mul_f32_e32 v57, v17, v17
	v_fmac_f32_e32 v54, v10, v10
	v_fmac_f32_e32 v55, v12, v12
	v_add_f32_e32 v49, v52, v53
	v_add_f32_e32 v46, v46, v48
	v_mul_f32_e32 v58, v3, v3
	v_mul_f32_e32 v59, v5, v5
	v_fmac_f32_e32 v56, v14, v14
	v_fmac_f32_e32 v57, v16, v16
	v_add_f32_e32 v50, v54, v55
	v_add_f32_e32 v46, v46, v49
	v_mul_f32_e32 v60, v7, v7
	v_mul_f32_e32 v61, v9, v9
	v_fmac_f32_e32 v58, v2, v2
	v_fmac_f32_e32 v59, v4, v4
	v_add_f32_e32 v51, v56, v57
	v_add_f32_e32 v46, v46, v50
	v_fmac_f32_e32 v60, v6, v6
	v_fmac_f32_e32 v61, v8, v8
	v_add_f32_e32 v52, v58, v59
	v_add_f32_e32 v46, v46, v51
	v_add_f32_e32 v46, v46, v52
	v_add_f32_e32 v47, v60, v61
	v_add_f32_e32 v46, v46, v47
	s_nop 1
	v_add_f32_dpp v46, v46, v46 quad_perm:[1,0,3,2] row_mask:0xf bank_mask:0xf
	s_nop 1
	v_add_f32_dpp v46, v46, v46 quad_perm:[2,3,0,1] row_mask:0xf bank_mask:0xf
	s_nop 1
	v_add_f32_dpp v46, v46, v46 row_half_mirror row_mask:0xf bank_mask:0xf
	s_nop 1
	v_add_f32_dpp v46, v46, v46 row_mirror row_mask:0xf bank_mask:0xf
	s_nop 1
	v_add_f32_dpp v46, v46, v46 row_bcast:15 row_mask:0xa bank_mask:0xf
	s_nop 1
	v_add_f32_dpp v46, v46, v46 row_bcast:31 row_mask:0xc bank_mask:0xf
	s_and_saveexec_b64 s[38:39], s[2:3]
	s_cbranch_execz .LBB0_88
	s_nop 1
	v_fmamk_f32 v46, v46, 0x3a000000, v44
	v_mul_f32_e32 v47, 0x4f800000, v46
	v_cmp_gt_f32_e32 vcc, s5, v46
	s_nop 1
	v_cndmask_b32_e32 v46, v46, v47, vcc
	v_sqrt_f32_e32 v47, v46
	s_nop 0
	v_add_u32_e32 v48, -1, v47
	v_fma_f32 v50, -v48, v47, v46
	v_add_u32_e32 v49, 1, v47
	v_cmp_ge_f32_e64 s[0:1], 0, v50
	s_nop 1
	v_cndmask_b32_e64 v48, v47, v48, s[0:1]
	v_fma_f32 v47, -v49, v47, v46
	v_cmp_lt_f32_e64 s[0:1], 0, v47
	s_nop 1
	v_cndmask_b32_e64 v47, v48, v49, s[0:1]
	v_mul_f32_e32 v48, 0x37800000, v47
	v_cndmask_b32_e32 v47, v47, v48, vcc
	v_cmp_class_f32_e32 vcc, v46, v45
	s_nop 1
	v_cndmask_b32_e32 v46, v47, v46, vcc
	v_div_scale_f32 v47, s[0:1], v46, v46, 1.0
	v_rcp_f32_e32 v48, v47
	s_add_u32 s0, s62, s40
	s_addc_u32 s1, s63, s41
	v_fma_f32 v49, -v47, v48, 1.0
	v_fmac_f32_e32 v48, v49, v48
	v_div_scale_f32 v49, vcc, 1.0, v46, 1.0
	v_mul_f32_e32 v50, v49, v48
	v_fma_f32 v51, -v47, v50, v49
	v_fmac_f32_e32 v50, v51, v48
	v_fma_f32 v47, -v47, v50, v49
	v_div_fmas_f32 v47, v47, v48, v50
	v_div_fixup_f32 v48, v47, v46, 1.0
	v_mov_b64_e32 v[46:47], s[0:1]
	flat_store_dword v[46:47], v48
	s_branch .LBB0_88

; __device__ __forceinline__ void p2_qk_norm_rope(const Ptrs& P, int gw, int NGW, int lane) {
;     ...
;     for (int row = gw; row < M_TOK; row += NGW) {
;         bf16* pq = P.Q + (size_t)row * 1024 + grp * 128 + sub * 8; bf16* pk = P.K + (size_t)row * 1024 + grp * 128 + sub * 8;
;         const v4u q1 = *(const v4u*)pq, q2 = *(const v4u*)(pq + 64), k1 = *(const v4u*)pk, k2 = *(const v4u*)(pk + 64);
;         const int pos = row & (SEQ - 1);
;         const f32x4 c0 = *(const f32x4*)(P.COS + pos * 64 + sub * 8), c1 = *(const f32x4*)(P.COS + pos * 64 + sub * 8 + 4);
;         const f32x4 s0 = *(const f32x4*)(P.SIN + pos * 64 + sub * 8), s1 = *(const f32x4*)(P.SIN + pos * 64 + sub * 8 + 4);
; #pragma unroll
;         for (int which = 0; which < 2; ++which) {
;             const v4u r1 = which ? k1 : q1, r2 = which ? k2 : q2;
;             float t1[8], t2[8];
; #pragma unroll
;             for (int j = 0; j < 4; ++j) { t1[2 * j] = bflo(r1[j]); t1[2 * j + 1] = bfhi(r1[j]); t2[2 * j] = bflo(r2[j]); t2[2 * j + 1] = bfhi(r2[j]); }
;             float ss = 0.f;
; #pragma unroll
;             for (int j = 0; j < 8; ++j) ss += t1[j] * t1[j] + t2[j] * t2[j];
;             ss += __shfl_xor(ss, 1); ss += __shfl_xor(ss, 2); ss += __shfl_xor(ss, 4);
;             const float rinv = (1.0f / sqrtf(ss * (1.f / HD) + EPS_RMS)) * (which ? 1.0f : QSCALE);
;             float o1[8], o2[8];
; #pragma unroll
;             for (int j = 0; j < 8; ++j) {
;                 const float cc = j < 4 ? c0[j & 3] : c1[j & 3], sn = j < 4 ? s0[j & 3] : s1[j & 3];
;                 const float ga = which ? (j < 4 ? gk[0][j & 3] : gk[1][j & 3]) : (j < 4 ? gq[0][j & 3] : gq[1][j & 3]);
;                 const float gb = which ? (j < 4 ? gk[2][j & 3] : gk[3][j & 3]) : (j < 4 ? gq[2][j & 3] : gq[3][j & 3]);
;                 const float n1 = t1[j] * rinv * ga, n2 = t2[j] * rinv * gb;
;                 o1[j] = n1 * cc - n2 * sn; o2[j] = n2 * cc + n1 * sn;
;             }
.LBB0_290:
	flat_load_dwordx4 v[70:73], v[46:47] offset:128
	flat_load_dwordx4 v[74:77], v[46:47]
	s_and_b32 s0, s36, 0x7ffc0
	s_lshl_b32 s6, s0, 2
	v_lshl_add_u64 v[36:37], v[44:45], 0, s[6:7]
	v_lshl_add_u64 v[34:35], v[42:43], 0, s[6:7]
	flat_load_dwordx4 v[22:25], v[36:37] offset:16
	flat_load_dwordx4 v[18:21], v[34:35] offset:16
	flat_load_dwordx4 v[30:33], v[36:37]
	flat_load_dwordx4 v[26:29], v[34:35]
	v_add_co_u32_e32 v64, vcc, 0x4000000, v46
	s_add_i32 s5, s5, s4
	s_nop 0
	v_addc_co_u32_e32 v65, vcc, 0, v47, vcc
	flat_load_dwordx4 v[34:37], v[64:65]
	flat_load_dwordx4 v[38:41], v[64:65] offset:128
	s_add_i32 s36, s36, s26
	s_cmp_lt_i32 s5, 0x8000
	s_waitcnt vmcnt(0) lgkmcnt(0)
	v_lshlrev_b32_e32 v85, 16, v73
	v_and_b32_e32 v69, 0xffff0000, v73
	v_lshlrev_b32_e32 v87, 16, v72
	v_and_b32_e32 v89, 0xffff0000, v72
	v_and_b32_e32 v93, 0xffff0000, v71
	v_and_b32_e32 v92, 0xffff0000, v75
	v_lshlrev_b32_e32 v95, 16, v70
	v_lshlrev_b32_e32 v94, 16, v74
	v_and_b32_e32 v97, 0xffff0000, v70
	v_and_b32_e32 v96, 0xffff0000, v74
	v_lshlrev_b32_e32 v84, 16, v77
	v_and_b32_e32 v68, 0xffff0000, v77
	v_lshlrev_b32_e32 v86, 16, v76
	v_and_b32_e32 v88, 0xffff0000, v76
	v_lshlrev_b32_e32 v91, 16, v71
	v_lshlrev_b32_e32 v90, 16, v75
	v_mov_b32_e32 v70, v69
	v_mov_b32_e32 v71, v85
	v_mov_b32_e32 v74, v89
	v_mov_b32_e32 v75, v87
	v_pk_mul_f32 v[98:99], v[92:93], v[92:93]
	v_pk_mul_f32 v[100:101], v[94:95], v[94:95]
	v_pk_mul_f32 v[102:103], v[96:97], v[96:97]
	v_mov_b32_e32 v66, v68
	v_mov_b32_e32 v67, v84
	v_mov_b32_e32 v72, v88
	v_mov_b32_e32 v73, v86
	v_pk_mul_f32 v[76:77], v[90:91], v[90:91]
	v_pk_mul_f32 v[70:71], v[70:71], v[70:71]
	v_pk_mul_f32 v[74:75], v[74:75], v[74:75]
	v_add_f32_e32 v83, v98, v99
	v_add_f32_e32 v98, v102, v103
	v_add_f32_e32 v99, v100, v101
	v_add_f32_e32 v76, v76, v77
	v_pk_fma_f32 v[66:67], v[66:67], v[66:67], v[70:71]
	v_pk_fma_f32 v[70:71], v[72:73], v[72:73], v[74:75]
	v_add_f32_e32 v72, v99, v98
	v_add_f32_e32 v72, v76, v72
	v_add_f32_e32 v72, v83, v72
	v_add_f32_e32 v71, v71, v72
	v_add_f32_e32 v70, v70, v71
	v_add_f32_e32 v67, v67, v70
	v_add_f32_e32 v72, v66, v67
	v_mov_b32_e32 v99, v32
	v_mov_b32_e32 v74, v30
	v_mov_b32_e32 v75, v26
	v_mov_b32_e32 v70, v22
	v_mov_b32_dpp v73, v72 quad_perm:[1,0,3,2] row_mask:0xf bank_mask:0xf
	v_add_f32_e32 v76, v72, v73
	v_mov_b32_e32 v73, v28
	v_mov_b32_e32 v72, v32
	v_mov_b32_e32 v32, v29
	v_mov_b32_e32 v71, v18
	v_mov_b32_dpp v77, v76 quad_perm:[2,3,0,1] row_mask:0xf bank_mask:0xf
	v_add_f32_e32 v83, v76, v77
	v_mov_b32_e32 v76, v26
	v_mov_b32_e32 v77, v30
	v_mov_b32_e32 v66, v24
	v_mov_b32_e32 v67, v20
	v_mov_b32_dpp v98, v83 row_half_mirror row_mask:0xf bank_mask:0xf
	v_add_f32_e32 v83, v83, v98
	v_fmamk_f32 v83, v83, 0x3c000000, v78
	v_mul_f32_e32 v98, 0x4f800000, v83
	v_cmp_gt_f32_e32 vcc, s27, v83
	v_mov_b32_e32 v30, v27
	v_mov_b32_e32 v26, v31
	v_cndmask_b32_e32 v83, v83, v98, vcc
	v_sqrt_f32_e32 v100, v83
	v_mov_b32_e32 v98, v28
	v_and_b32_e32 v113, 0xffff0000, v38
	v_and_b32_e32 v112, 0xffff0000, v34
	v_add_u32_e32 v28, -1, v100
	v_add_u32_e32 v101, 1, v100
	v_fma_f32 v102, -v28, v100, v83
	v_fma_f32 v103, -v101, v100, v83
	v_cmp_ge_f32_e64 s[0:1], 0, v102
	s_nop 1
	v_cndmask_b32_e64 v28, v100, v28, s[0:1]
	v_cmp_lt_f32_e64 s[0:1], 0, v103
	s_nop 1
	v_cndmask_b32_e64 v28, v28, v101, s[0:1]
	v_mul_f32_e32 v100, 0x37800000, v28
	v_cndmask_b32_e32 v28, v28, v100, vcc
	v_cmp_class_f32_e32 vcc, v83, v79
	s_nop 1
	v_cndmask_b32_e32 v83, v28, v83, vcc
	v_div_scale_f32 v100, s[0:1], v83, v83, 1.0
	v_rcp_f32_e32 v101, v100
	v_div_scale_f32 v102, vcc, 1.0, v83, 1.0
	v_mov_b32_e32 v28, v33
	v_fma_f32 v103, -v100, v101, 1.0
	v_fmac_f32_e32 v101, v103, v101
	v_mul_f32_e32 v103, v102, v101
	v_fma_f32 v104, -v100, v103, v102
	v_fmac_f32_e32 v103, v104, v101
	v_fma_f32 v100, -v100, v103, v102
	v_div_fmas_f32 v100, v100, v101, v103
	v_div_fixup_f32 v83, v100, v83, 1.0
	v_mul_f32_e32 v100, 0x3e0293ee, v83
	v_pk_mul_f32 v[90:91], v[100:101], v[90:91] op_sel_hi:[0,1]
	v_pk_mul_f32 v[94:95], v[100:101], v[94:95] op_sel_hi:[0,1]
	v_pk_mul_f32 v[92:93], v[100:101], v[92:93] op_sel_hi:[0,1]
	v_pk_mul_f32 v[90:91], v[52:53], v[90:91]
	v_pk_mul_f32 v[86:87], v[100:101], v[86:87] op_sel_hi:[0,1]
	v_pk_mul_f32 v[94:95], v[54:55], v[94:95]
	v_pk_mul_f32 v[92:93], v[8:9], v[92:93]
	v_pk_mul_f32 v[106:107], v[98:99], v[90:91]
	v_pk_mul_f32 v[90:91], v[72:73], v[90:91]
	v_pk_mul_f32 v[86:87], v[50:51], v[86:87]
	v_pk_mul_f32 v[102:103], v[76:77], v[94:95]
	v_pk_mul_f32 v[94:95], v[74:75], v[94:95]
	v_pk_mul_f32 v[108:109], v[32:33], v[92:93]
	v_pk_mul_f32 v[92:93], v[28:29], v[92:93]
	v_add_f32_e32 v117, v90, v91
	v_mov_b32_e32 v90, v18
	v_mov_b32_e32 v91, v22
	v_pk_mul_f32 v[96:97], v[100:101], v[96:97] op_sel_hi:[0,1]
	v_add_f32_e32 v101, v94, v95
	v_add_f32_e32 v119, v92, v93
	v_pk_mul_f32 v[92:93], v[90:91], v[86:87]
	v_pk_mul_f32 v[86:87], v[70:71], v[86:87]
	v_mov_b32_e32 v22, v19
	v_add_f32_e32 v121, v86, v87
	v_pk_mul_f32 v[86:87], v[100:101], v[88:89] op_sel_hi:[0,1]
	v_pk_mul_f32 v[86:87], v[2:3], v[86:87]
	v_mov_b32_e32 v18, v23
	v_pk_mul_f32 v[88:89], v[22:23], v[86:87]
	v_pk_mul_f32 v[86:87], v[18:19], v[86:87]
	v_pk_mul_f32 v[84:85], v[100:101], v[84:85] op_sel_hi:[0,1]
	v_add_f32_e32 v123, v86, v87
	v_pk_mul_f32 v[84:85], v[48:49], v[84:85]
	v_mov_b32_e32 v86, v20
	v_mov_b32_e32 v87, v24
	v_sub_f32_e32 v122, v88, v89
	v_pk_mul_f32 v[88:89], v[86:87], v[84:85]
	v_pk_mul_f32 v[84:85], v[66:67], v[84:85]
	v_sub_f32_e32 v124, v88, v89
	v_add_f32_e32 v125, v84, v85
	v_lshlrev_b32_e32 v85, 16, v41
	v_and_b32_e32 v89, 0xffff0000, v41
	v_pk_mul_f32 v[96:97], v[6:7], v[96:97]
; __device__ __forceinline__ unsigned pk2(float lo, float hi) { return pg8::cvt_pk_bf16(lo, hi); }
; __device__ __forceinline__ void p2_qk_norm_rope(const Ptrs& P, int gw, int NGW, int lane) {
;     ...
;         for (int which = 0; which < 2; ++which) {
;             const v4u r1 = which ? k1 : q1, r2 = which ? k2 : q2;
;             float t1[8], t2[8];
; #pragma unroll
;             for (int j = 0; j < 4; ++j) { t1[2 * j] = bflo(r1[j]); t1[2 * j + 1] = bfhi(r1[j]); t2[2 * j] = bflo(r2[j]); t2[2 * j + 1] = bfhi(r2[j]); }
;             float ss = 0.f;
; #pragma unroll
;             for (int j = 0; j < 8; ++j) ss += t1[j] * t1[j] + t2[j] * t2[j];
;             ss += __shfl_xor(ss, 1); ss += __shfl_xor(ss, 2); ss += __shfl_xor(ss, 4);
;             const float rinv = (1.0f / sqrtf(ss * (1.f / HD) + EPS_RMS)) * (which ? 1.0f : QSCALE);
;             float o1[8], o2[8];
; #pragma unroll
;             for (int j = 0; j < 8; ++j) {
;                 const float cc = j < 4 ? c0[j & 3] : c1[j & 3], sn = j < 4 ? s0[j & 3] : s1[j & 3];
;                 const float ga = which ? (j < 4 ? gk[0][j & 3] : gk[1][j & 3]) : (j < 4 ? gq[0][j & 3] : gq[1][j & 3]);
;                 const float gb = which ? (j < 4 ? gk[2][j & 3] : gk[3][j & 3]) : (j < 4 ? gq[2][j & 3] : gq[3][j & 3]);
;                 const float n1 = t1[j] * rinv * ga, n2 = t2[j] * rinv * gb;
;                 o1[j] = n1 * cc - n2 * sn; o2[j] = n2 * cc + n1 * sn;
;             }
;             v4u w1, w2;
; #pragma unroll
;             for (int j = 0; j < 4; ++j) { w1[j] = pk2(o1[2 * j], o1[2 * j + 1]); w2[j] = pk2(o2[2 * j], o2[2 * j + 1]); }
;             bf16* p = which ? pk : pq;
;             *(v4u*)p = w1; *(v4u*)(p + 64) = w2;
	v_lshlrev_b32_e32 v84, 16, v37
	v_and_b32_e32 v88, 0xffff0000, v37
	v_mov_b32_e32 v94, v89
	v_mov_b32_e32 v95, v85
	v_pk_mul_f32 v[104:105], v[30:31], v[96:97]
	v_pk_mul_f32 v[96:97], v[26:27], v[96:97]
	v_sub_f32_e32 v120, v92, v93
	v_mov_b32_e32 v92, v88
	v_mov_b32_e32 v93, v84
	v_pk_mul_f32 v[94:95], v[94:95], v[94:95]
	v_add_f32_e32 v115, v96, v97
	v_pk_fma_f32 v[92:93], v[92:93], v[92:93], v[94:95]
	v_lshlrev_b32_e32 v95, 16, v40
	v_and_b32_e32 v97, 0xffff0000, v40
	v_sub_f32_e32 v118, v108, v109
	v_lshlrev_b32_e32 v94, 16, v36
	v_and_b32_e32 v96, 0xffff0000, v36
	v_mov_b32_e32 v40, v97
	v_mov_b32_e32 v41, v95
	v_lshlrev_b32_e32 v109, 16, v38
	v_lshlrev_b32_e32 v108, 16, v34
	v_sub_f32_e32 v83, v102, v103
	v_sub_f32_e32 v114, v104, v105
	v_mov_b32_e32 v36, v96
	v_mov_b32_e32 v37, v94
	v_pk_mul_f32 v[40:41], v[40:41], v[40:41]
	v_lshlrev_b32_e32 v103, 16, v39
	v_lshlrev_b32_e32 v102, 16, v35
	v_and_b32_e32 v104, 0xffff0000, v35
	v_pk_mul_f32 v[110:111], v[108:109], v[108:109]
	v_pk_mul_f32 v[34:35], v[112:113], v[112:113]
	v_pk_fma_f32 v[36:37], v[36:37], v[36:37], v[40:41]
	v_pk_mul_f32 v[40:41], v[102:103], v[102:103]
	v_and_b32_e32 v105, 0xffff0000, v39
	v_add_f32_e32 v24, v34, v35
	v_add_f32_e32 v34, v110, v111
	v_sub_f32_e32 v116, v106, v107
	v_pk_mul_f32 v[106:107], v[104:105], v[104:105]
	v_add_f32_e32 v24, v34, v24
	v_add_f32_e32 v34, v40, v41
	v_add_f32_e32 v20, v106, v107
	v_add_f32_e32 v24, v34, v24
	v_add_f32_e32 v20, v20, v24
	v_add_f32_e32 v20, v37, v20
	v_add_f32_e32 v20, v36, v20
	v_add_f32_e32 v20, v93, v20
	v_add_f32_e32 v20, v92, v20
	v_pk_mul_f32 v[34:35], v[100:101], v[68:69] op_sel_hi:[0,1]
	v_pk_mul_f32 v[34:35], v[4:5], v[34:35]
	v_mov_b32_e32 v24, v21
	v_pk_mul_f32 v[36:37], v[24:25], v[34:35]
	v_mov_b32_dpp v38, v20 quad_perm:[1,0,3,2] row_mask:0xf bank_mask:0xf
	v_add_f32_e32 v38, v20, v38
	v_sub_f32_e32 v37, v36, v37
	v_mov_b32_e32 v20, v25
	v_pk_mul_f32 v[34:35], v[20:21], v[34:35]
	v_mov_b32_dpp v39, v38 quad_perm:[2,3,0,1] row_mask:0xf bank_mask:0xf
	v_add_f32_e32 v36, v38, v39
	v_add_f32_e32 v41, v34, v35
	v_cvt_pk_bf16_f32 v34, v83, v114
	v_cvt_pk_bf16_f32 v38, v101, v115
	v_cvt_pk_bf16_f32 v35, v116, v118
	v_mov_b32_dpp v40, v36 row_half_mirror row_mask:0xf bank_mask:0xf
	v_add_f32_e32 v36, v36, v40
	v_fmamk_f32 v36, v36, 0x3c000000, v78
	v_mul_f32_e32 v40, 0x4f800000, v36
	v_cmp_gt_f32_e32 vcc, s27, v36
	v_cvt_pk_bf16_f32 v39, v117, v119
	s_nop 1
	v_cndmask_b32_e32 v68, v36, v40, vcc
	v_sqrt_f32_e32 v69, v68
	v_cvt_pk_bf16_f32 v36, v120, v122
	v_cvt_pk_bf16_f32 v40, v121, v123
	v_cvt_pk_bf16_f32 v37, v124, v37
	v_cvt_pk_bf16_f32 v41, v125, v41
	flat_store_dwordx4 v[46:47], v[34:37]
	flat_store_dwordx4 v[46:47], v[38:41] offset:128
	v_add_u32_e32 v83, -1, v69
	v_fma_f32 v92, -v83, v69, v68
	v_cmp_ge_f32_e64 s[0:1], 0, v92
	v_add_u32_e32 v92, 1, v69
	v_lshl_add_u64 v[46:47], v[46:47], 0, s[24:25]
	v_cndmask_b32_e64 v83, v69, v83, s[0:1]
	v_fma_f32 v69, -v92, v69, v68
	v_cmp_lt_f32_e64 s[0:1], 0, v69
	s_nop 1
	v_cndmask_b32_e64 v69, v83, v92, s[0:1]
	v_mul_f32_e32 v83, 0x37800000, v69
	v_cndmask_b32_e32 v69, v69, v83, vcc
	v_cmp_class_f32_e32 vcc, v68, v79
	s_nop 1
	v_cndmask_b32_e32 v68, v69, v68, vcc
	v_div_scale_f32 v69, s[0:1], v68, v68, 1.0
	v_rcp_f32_e32 v83, v69
	s_nop 0
	v_fma_f32 v34, -v69, v83, 1.0
	v_fmac_f32_e32 v83, v34, v83
	v_div_scale_f32 v34, vcc, 1.0, v68, 1.0
	v_mul_f32_e32 v35, v34, v83
	v_fma_f32 v36, -v69, v35, v34
	v_fmac_f32_e32 v35, v36, v83
	v_fma_f32 v34, -v69, v35, v34
	v_div_fmas_f32 v34, v34, v83, v35
	v_div_fixup_f32 v34, v34, v68, 1.0
	v_pk_mul_f32 v[36:37], v[34:35], v[108:109] op_sel_hi:[0,1]
	v_pk_mul_f32 v[36:37], v[62:63], v[36:37]
	s_nop 0
	v_pk_mul_f32 v[38:39], v[76:77], v[36:37]
	v_pk_mul_f32 v[36:37], v[74:75], v[36:37]
	v_sub_f32_e32 v35, v38, v39
	v_add_f32_e32 v38, v36, v37
	v_pk_mul_f32 v[36:37], v[34:35], v[112:113] op_sel_hi:[0,1]
	v_pk_mul_f32 v[36:37], v[14:15], v[36:37]
	s_nop 0
	v_pk_mul_f32 v[26:27], v[26:27], v[36:37]
	v_pk_mul_f32 v[30:31], v[30:31], v[36:37]
	v_add_f32_e32 v36, v26, v27
	v_pk_mul_f32 v[26:27], v[34:35], v[102:103] op_sel_hi:[0,1]
	v_pk_mul_f32 v[26:27], v[60:61], v[26:27]
	v_sub_f32_e32 v39, v30, v31
	v_pk_mul_f32 v[30:31], v[98:99], v[26:27]
	v_pk_mul_f32 v[26:27], v[72:73], v[26:27]
	v_sub_f32_e32 v37, v30, v31
	v_add_f32_e32 v40, v26, v27
	v_pk_mul_f32 v[26:27], v[34:35], v[104:105] op_sel_hi:[0,1]
	v_pk_mul_f32 v[26:27], v[16:17], v[26:27]
	s_nop 0
	v_pk_mul_f32 v[30:31], v[32:33], v[26:27]
	v_pk_mul_f32 v[26:27], v[28:29], v[26:27]
	v_sub_f32_e32 v30, v30, v31
	v_add_f32_e32 v31, v26, v27
	v_pk_mul_f32 v[26:27], v[34:35], v[94:95] op_sel_hi:[0,1]
	v_pk_mul_f32 v[26:27], v[58:59], v[26:27]
	s_nop 0
	v_pk_mul_f32 v[28:29], v[90:91], v[26:27]
	v_pk_mul_f32 v[26:27], v[70:71], v[26:27]
	v_sub_f32_e32 v28, v28, v29
	v_add_f32_e32 v29, v26, v27
	v_pk_mul_f32 v[26:27], v[34:35], v[96:97] op_sel_hi:[0,1]
	v_pk_mul_f32 v[26:27], v[10:11], v[26:27]
	s_nop 0
	v_pk_mul_f32 v[18:19], v[18:19], v[26:27]
	v_pk_mul_f32 v[22:23], v[22:23], v[26:27]
	v_add_f32_e32 v26, v18, v19
	v_pk_mul_f32 v[18:19], v[34:35], v[84:85] op_sel_hi:[0,1]
	v_pk_mul_f32 v[18:19], v[56:57], v[18:19]
	v_sub_f32_e32 v32, v22, v23
	v_pk_mul_f32 v[22:23], v[86:87], v[18:19]
	v_pk_mul_f32 v[18:19], v[66:67], v[18:19]
	v_sub_f32_e32 v27, v22, v23
	v_add_f32_e32 v33, v18, v19
	v_pk_mul_f32 v[18:19], v[34:35], v[88:89] op_sel_hi:[0,1]
	v_pk_mul_f32 v[18:19], v[12:13], v[18:19]
	s_nop 0
	v_pk_mul_f32 v[22:23], v[24:25], v[18:19]
	v_pk_mul_f32 v[18:19], v[20:21], v[18:19]
	v_sub_f32_e32 v25, v22, v23
	v_add_f32_e32 v34, v18, v19
	v_cvt_pk_bf16_f32 v18, v35, v39
	v_cvt_pk_bf16_f32 v22, v38, v36
	v_cvt_pk_bf16_f32 v19, v37, v30
	v_cvt_pk_bf16_f32 v23, v40, v31
	v_cvt_pk_bf16_f32 v20, v28, v32
	v_cvt_pk_bf16_f32 v24, v29, v26
	v_cvt_pk_bf16_f32 v21, v27, v25
	v_cvt_pk_bf16_f32 v25, v33, v34
	flat_store_dwordx4 v[64:65], v[18:21]
	flat_store_dwordx4 v[64:65], v[22:25] offset:128
	s_cbranch_scc1 .LBB0_290
